# grid barrier: non-leader workgroups poll the top-level generation word directly instead of waiting for their XCD leader's relay (one dependent round trip fewer per barrier)
# speedup vs baseline: 1.0045x; 1.0045x over previous
.LBB0_635:
	s_or_b64 exec, exec, s[2:3]
	v_cvt_f32_u32_e32 v5, v3
	s_waitcnt vmcnt(0)
	v_readfirstlane_b32 s2, v4
	v_sub_u32_e32 v4, 0, v3
	v_rcp_iflag_f32_e32 v5, v5
	v_add_u32_e32 v6, s2, v0
	v_mul_f32_e32 v5, 0x4f7ffffe, v5
	v_cvt_u32_f32_e32 v5, v5
	v_mul_lo_u32 v0, v4, v5
	v_mul_hi_u32 v0, v5, v0
	v_add_u32_e32 v0, v5, v0
	v_mul_hi_u32 v0, v6, v0
	v_mul_lo_u32 v4, v0, v3
	v_sub_u32_e32 v4, v6, v4
	v_add_u32_e32 v5, 1, v0
	v_cmp_ge_u32_e32 vcc, v4, v3
	s_nop 1
	v_cndmask_b32_e32 v0, v0, v5, vcc
	v_sub_u32_e32 v5, v4, v3
	v_cndmask_b32_e32 v4, v4, v5, vcc
	v_add_u32_e32 v5, 1, v0
	v_cmp_ge_u32_e32 vcc, v4, v3
	v_add_u32_e32 v4, 1, v6
	s_nop 0
	v_cndmask_b32_e32 v0, v0, v5, vcc
	v_mul_lo_u32 v5, v3, v0
	v_add_u32_e32 v3, v5, v3
	v_cmp_ne_u32_e32 vcc, v4, v3
	s_and_saveexec_b64 s[2:3], vcc
	s_xor_b64 s[2:3], exec, s[2:3]
	s_cbranch_execz .LBB0_649
	v_readlane_b32 s4, v253, 46
	v_readlane_b32 s5, v253, 47
	s_waitcnt lgkmcnt(0)
	s_nop 3
	global_load_dword v2, v1, s[4:5] sc1
	s_waitcnt vmcnt(0)
	v_cmp_eq_u32_e32 vcc, v2, v0
	s_and_saveexec_b64 s[4:5], vcc
	s_cbranch_execz .LBB0_648
	s_mov_b32 s20, 1
	s_mov_b64 s[6:7], 0
	s_branch .LBB0_639
